# on top: first conv batch issued with the conv weights; uniform-bias iterations add the bias with a broadcast operand; rel-pos bias table loads issued ahead of the phase set-up
# baseline (speedup 1.0000x reference)
.LBB0_12:
	s_mov_b64 s[84:85], s[0:1]
	v_mov_b32_e32 v164, v137
	s_mov_b32 s12, s2
	s_mov_b32 s80, s46
	s_cmp_lg_u32 s68, 15
	s_mov_b64 s[14:15], -1
	s_cbranch_scc0 .LBB0_568
	v_sub_co_u32_e64 v0, s[18:19], s68, 1
	s_nop 0
	v_readfirstlane_b32 s13, v0
	s_mul_hi_i32 s14, s13, 0x92492493
	s_add_i32 s14, s14, s13
	s_lshr_b32 s15, s14, 31
	s_ashr_i32 s14, s14, 2
	s_add_i32 s14, s14, s15
	s_mul_i32 s15, s14, 7
	s_sub_i32 s13, s13, s15
	s_and_b64 s[16:17], s[18:19], exec
	s_cselect_b32 s13, 2, s13
	s_cmp_lg_u32 s13, 0
	s_cselect_b64 s[24:25], -1, 0
	s_cmp_lt_i32 s13, 4
	s_cselect_b64 s[16:17], -1, 0
	v_writelane_b32 v255, s24, 6
	s_and_b64 s[16:17], s[24:25], s[16:17]
	s_mov_b64 s[20:21], -1
	v_writelane_b32 v255, s25, 7
	s_and_b64 vcc, exec, s[16:17]
	s_cbranch_vccz .LBB0_448
	s_mov_b64 s[22:23], -1
	s_mov_b64 s[44:45], 0
	s_cmp_lt_i32 s13, 2
	s_mov_b64 s[20:21], 0
	s_movk_i32 s1, 0x1000
	s_movk_i32 s2, 0x100
	s_cbranch_scc1 .LBB0_141
	s_cmp_eq_u32 s13, 2
	s_mov_b64 s[20:21], -1
	s_cbranch_scc0 .LBB0_335
	s_load_dwordx2 s[20:21], s[84:85], 0xa8
	s_load_dwordx8 s[52:59], s[84:85], 0x0
	v_readfirstlane_b32 s15, v164
	s_xor_b64 s[16:17], s[18:19], -1
	s_ashr_i32 s37, s15, 6
	s_waitcnt lgkmcnt(0)
	s_add_u32 s18, s20, 0x400000
	v_and_b32_e32 v229, 63, v164
	s_addc_u32 s19, s21, 0
	s_and_b64 vcc, exec, s[16:17]
	s_cbranch_vccz .LBB0_252
	s_load_dwordx8 s[60:67], s[84:85], 0x70
	s_mul_i32 s26, s14, 0x404
	v_add_u32_e32 v0, s26, v164
	v_ashrrev_i32_e32 v1, 31, v0
	v_lshl_add_u64 v[0:1], v[0:1], 2, s[58:59]
	s_mov_b64 s[16:17], 0x1000
	v_lshl_add_u64 v[2:3], v[0:1], 0, s[16:17]
	global_load_dword v250, v[0:1], off
	global_load_dword v251, v[0:1], off offset:2048
	v_cmp_gt_u32_e32 vcc, 4, v164
	s_and_saveexec_b64 s[24:25], vcc
	global_load_dword v252, v[2:3], off
	s_or_b64 exec, exec, s[24:25]
	s_and_b32 s15, s80, 7
	s_cmp_eq_u32 s15, 0
	s_mov_b32 s96, s12
	s_cbranch_scc0 .LBB0_32
	s_and_b32 s15, s12, 7
	s_ashr_i32 s16, s80, 3
	s_mul_i32 s15, s16, s15
	s_ashr_i32 s16, s12, 3
	s_add_i32 s96, s15, s16
.LBB0_32:
	s_add_u32 s24, s20, 0x7600000
	s_addc_u32 s25, s21, 0
	s_add_u32 s46, s20, 0x280000
	s_addc_u32 s47, s21, 0
	s_bfe_u32 s15, s12, 0x10007
	v_mov_b32_e32 v0, 0x6050400
	s_lshl_b32 s16, s15, 24
	v_perm_b32 v165, s12, v164, v0
	s_add_u32 s16, s24, s16
	v_and_b32_e32 v0, 0x7fff, v165
	s_addc_u32 s17, s25, 0
	s_lshl_b32 s15, s15, 12
	v_lshlrev_b32_e32 v162, 2, v0
	s_add_u32 s15, s46, s15
	v_lshl_add_u64 v[166:167], s[16:17], 0, v[162:163]
	s_addc_u32 s16, s47, 0
	s_lshr_b32 s17, s12, 2
	s_and_b32 s17, s17, 28
	s_mov_b32 s0, 0x10000
	v_cmp_gt_i32_e64 s[22:23], s2, v164
	s_add_u32 s58, s15, s17
	v_cmp_gt_i32_e32 vcc, s0, v165
	s_addc_u32 s59, s16, 0
	s_and_b64 s[16:17], s[22:23], vcc
	v_cndmask_b32_e64 v168, v219, 0, s[16:17]
	v_readfirstlane_b32 s88, v164
	v_lshrrev_b32_e32 v246, 6, v164
	v_and_b32_e32 v246, 3, v246
	v_lshlrev_b32_e32 v246, 13, v246
	v_add_u32_e32 v246, 0x1b000, v246
	s_lshr_b32 s73, s88, 6
	s_and_b32 s73, s73, 3
	s_lshl_b32 s73, s73, 13
	s_add_i32 s73, s73, 0x1b000
	s_lshr_b32 s88, s88, 8
	v_lshl_add_u32 v246, v229, 2, v246
	s_mov_b32 s89, 0
	s_mov_b32 s94, 0
	s_mov_b32 s95, 0
	s_add_i32 s15, s68, 5
	s_lshl_b32 s81, s80, 2
	s_lshl_b32 s16, s12, 2
	s_cmp_lt_u32 s15, 13
	s_movk_i32 s15, 0x3d00
	s_cselect_b32 s15, s15, 0x6200
	s_movk_i32 s17, 0x3500
	s_cselect_b32 s17, s17, 0x5e00
	v_mov_b32_e32 v1, s15
	s_movk_i32 s15, 0xbfc
	v_mov_b32_e32 v0, s17
	s_cselect_b32 s15, s15, 0x3cfc
	v_cndmask_b32_e64 v230, v0, v1, s[22:23]
	v_mov_b32_e32 v1, s15
	v_writelane_b32 v255, s22, 8
	s_add_i32 s15, s37, s16
	v_lshrrev_b32_e32 v232, 2, v229
	v_cndmask_b32_e64 v0, v1, v0, s[22:23]
	v_add_u32_e32 v231, s15, v0
	v_mov_b32_e32 v231, v230
	s_mul_i32 s15, s37, 0x1100
	s_add_i32 s15, s15, 0
	v_writelane_b32 v255, s23, 9
	s_add_i32 s22, s15, 0x12800
	s_add_u32 s26, s20, 0x1000000
	s_addc_u32 s27, s21, 0
	s_add_u32 s28, s20, 0x1400000
	s_addc_u32 s29, s21, 0
	s_add_u32 s30, s20, 0x2a00000
	s_addc_u32 s31, s21, 0
	s_cmpk_gt_i32 s96, 0xff
	v_and_b32_e32 v235, 60, v229
	v_or_b32_e32 v233, 16, v232
	v_writelane_b32 v255, s37, 10
	s_cbranch_scc1 .LBB0_144
	s_add_u32 s98, s20, 0x5600000
	s_addc_u32 s99, s21, 0
	v_lshlrev_b32_e32 v1, 3, v229
	s_add_u32 s15, s20, 0x9600000
	v_and_b32_e32 v0, 31, v164
	v_lshrrev_b32_e32 v178, 5, v229
	v_and_b32_e32 v18, 24, v1
	s_addc_u32 s40, s21, 0
	v_lshl_add_u32 v19, v0, 2, s22
	v_mul_u32_u24_e32 v20, 0x84, v178
	v_mul_u32_u24_e32 v1, 0x84, v18
	s_lshl_b32 s16, s96, 6
	v_writelane_b32 v255, s22, 11
	v_add3_u32 v1, s22, v1, v235
	v_cmp_gt_u32_e64 s[42:43], 8, v0
	v_mov_b32_e32 v179, v163
	s_add_i32 s41, s16, 0xfffffe40
	s_lshl_b32 s22, s80, 6
	v_mov_b32_e32 v176, v163
	v_mov_b32_e32 v177, v163
	v_mov_b32_e32 v2, v163
	v_mov_b32_e32 v3, v163
	v_mov_b32_e32 v4, v163
	v_mov_b32_e32 v5, v163
	v_mov_b32_e32 v6, v163
	v_mov_b32_e32 v7, v163
	v_mov_b32_e32 v8, v163
	v_mov_b32_e32 v9, v163
	v_mov_b32_e32 v10, v163
	v_mov_b32_e32 v11, v163
	v_mov_b32_e32 v12, v163
	v_mov_b32_e32 v13, v163
	v_mov_b32_e32 v14, v163
	v_mov_b32_e32 v15, v163
	v_mov_b32_e32 v16, v163
	v_mov_b32_e32 v17, v163
	v_mov_b32_e32 v234, 0x400
	v_mov_b32_e32 v236, 0
	s_mov_b64 s[36:37], 0
	v_mov_b64_e32 v[170:171], s[18:19]
	v_mov_b64_e32 v[172:173], s[54:55]
	v_lshlrev_b32_e32 v162, 2, v0
	v_lshlrev_b32_e32 v180, 1, v18
	v_add_u32_e32 v237, v19, v20
	v_mov_b32_e32 v0, 0
	v_mov_b32_e32 v174, 0
	s_branch .LBB0_35

.LBB0_35:
	v_mov_b32_e32 v44, v164
	s_lshl_b32 s35, s96, 6
	v_readfirstlane_b32 s34, v44
	v_and_b32_e32 v45, 15, v44
	s_ashr_i32 s38, s34, 7
	s_lshr_b32 s16, s34, 1
	v_and_or_b32 v78, s16, 32, v45
	s_lshl_b32 s16, s38, 6
	s_ashr_i32 s17, s16, 31
	s_lshl_b64 s[92:93], s[16:17], 1
	s_add_u32 s16, s15, s92
	v_or_b32_e32 v186, s35, v78
	s_addc_u32 s17, s40, s93
	v_and_b32_e32 v18, 48, v44
	v_mov_b32_e32 v19, v163
	v_lshl_add_u64 v[20:21], s[16:17], 0, v[18:19]
	v_or_b32_e32 v182, 16, v186
	v_mad_i64_i32 v[22:23], s[16:17], v186, s76, v[20:21]
	v_mad_i64_i32 v[20:21], s[16:17], v182, s76, v[20:21]
	s_and_b32 s16, s96, 0x7f
	s_sub_i32 s17, 8, s16
	s_cmp_lt_u32 s16, 8
	s_cselect_b32 s23, s17, 0
	s_lshl_b32 s39, s23, 6
	s_add_i32 s16, s35, s39
	s_addk_i32 s16, 0xfe00
	global_load_dwordx4 v[26:29], v[22:23], off
	global_load_dwordx4 v[30:33], v[22:23], off offset:64
	v_add_u32_e32 v22, 0x200, v44
	s_mul_hi_i32 s17, s16, 0x1600
	s_mulk_i32 s16, 0x1600
	v_ashrrev_i32_e32 v79, 5, v22
	v_add_u32_e32 v22, 0x400, v44
	s_add_u32 s16, s15, s16
	v_lshlrev_b32_e32 v19, 3, v44
	v_ashrrev_i32_e32 v80, 5, v22
	v_add_u32_e32 v22, 0x600, v44
	s_addc_u32 s17, s40, s17
	global_load_dwordx4 v[34:37], v[20:21], off
	global_load_dwordx4 v[38:41], v[20:21], off offset:64
	v_and_b32_e32 v20, 0xf8, v19
	v_ashrrev_i32_e32 v81, 5, v22
	v_mov_b64_e32 v[22:23], s[16:17]
	v_mad_i64_i32 v[24:25], s[16:17], v81, s76, v[22:23]
	v_lshlrev_b32_e32 v42, 1, v20
	v_mov_b32_e32 v43, v163
	v_lshl_add_u64 v[24:25], v[24:25], 0, v[42:43]
	global_load_dwordx4 v[62:65], v[24:25], off offset:1024
	global_load_dwordx4 v[46:49], v[24:25], off offset:512
	v_mad_i64_i32 v[24:25], s[16:17], v80, s76, v[22:23]
	v_ashrrev_i32_e32 v21, 5, v44
	v_lshl_add_u64 v[24:25], v[24:25], 0, v[42:43]
	global_load_dwordx4 v[66:69], v[24:25], off offset:1024
	global_load_dwordx4 v[50:53], v[24:25], off offset:512
	v_mad_i64_i32 v[24:25], s[16:17], v79, s76, v[22:23]
	v_mad_i64_i32 v[22:23], s[16:17], v21, s76, v[22:23]
	v_lshl_add_u64 v[24:25], v[24:25], 0, v[42:43]
	v_lshl_add_u64 v[22:23], v[22:23], 0, v[42:43]
	global_load_dwordx4 v[70:73], v[24:25], off offset:1024
	global_load_dwordx4 v[54:57], v[24:25], off offset:512
	global_load_dwordx4 v[74:77], v[22:23], off offset:1024
	global_load_dwordx4 v[58:61], v[22:23], off offset:512
	v_lshlrev_b32_e32 v24, 2, v44
	s_movk_i32 s0, 0x80
	v_bitop3_b32 v239, v24, 64, v213 bitop3:0x6c
	v_bitop3_b32 v238, v24, s0, v213 bitop3:0x6c
	v_lshrrev_b32_e32 v24, 2, v44
	v_mad_i64_i32 v[188:189], s[16:17], v21, s76, 0
	v_mad_i64_i32 v[190:191], s[16:17], v79, s76, 0
	v_mad_i64_i32 v[192:193], s[16:17], v80, s76, 0
	v_mad_i64_i32 v[194:195], s[16:17], v81, s76, 0
	v_bfe_u32 v23, v44, 2, 2
	v_and_b32_e32 v240, 12, v24
	v_add_u32_e32 v22, 0, v42
	s_and_b32 s16, s34, 0xffffff80
	v_or_b32_e32 v23, v240, v23
	s_add_i32 s17, s16, 0
	v_mad_u64_u32 v[196:197], s[34:35], v21, s77, v[22:23]
	v_mad_u64_u32 v[198:199], s[34:35], v79, s77, v[22:23]
	v_mad_u64_u32 v[200:201], s[34:35], v80, s77, v[22:23]
	v_mad_u64_u32 v[202:203], s[34:35], v81, s77, v[22:23]
	v_mul_u32_u24_e32 v22, 0x210, v23
	v_and_b32_e32 v19, 24, v19
	s_mulk_i32 s38, 0x404
	v_add3_u32 v197, s17, v22, v19
	v_or_b32_e32 v19, 0x1d0, v78
	v_add_u32_e32 v18, s17, v18
	s_add_i32 s16, s38, 0
	v_mul_u32_u24_e32 v21, 0x210, v45
	v_sub_u32_e32 v19, v19, v240
	v_ashrrev_i32_e32 v187, 31, v186
	v_ashrrev_i32_e32 v183, 31, v182
	s_add_i32 s16, s16, 0x23000
	v_add_u32_e32 v199, 0xa400, v197
	v_subrev_u32_e32 v201, s39, v19
	s_add_i32 s17, s41, s39
	v_mov_b32_e32 v181, 0xf149f2ca
	v_lshlrev_b32_e32 v204, 1, v20
	v_add_u32_e32 v203, v18, v21
	v_mov_b32_e32 v175, 0xf149f2ca
	s_mov_b64 s[34:35], s[36:37]
	v_mov_b32_e32 v78, 0
	v_mov_b32_e32 v79, v236
	v_mov_b32_e32 v80, v236
	v_mov_b32_e32 v81, v236
	v_mov_b32_e32 v94, 0
	v_mov_b32_e32 v95, v236
	v_mov_b32_e32 v96, v236
	v_mov_b32_e32 v97, v236
	v_mov_b32_e32 v42, 0
	v_mov_b32_e32 v43, v236
	v_mov_b32_e32 v44, v236
	v_mov_b32_e32 v45, v236
	v_mov_b32_e32 v90, 0
	v_mov_b32_e32 v91, v236
	v_mov_b32_e32 v92, v236
	v_mov_b32_e32 v93, v236
	v_mov_b32_e32 v18, 0
	v_mov_b32_e32 v19, v236
	v_mov_b32_e32 v20, v236
	v_mov_b32_e32 v21, v236
	v_mov_b32_e32 v82, 0
	v_mov_b32_e32 v83, v236
	v_mov_b32_e32 v84, v236
	v_mov_b32_e32 v85, v236
	v_mov_b32_e32 v22, 0
	v_mov_b32_e32 v23, v236
	v_mov_b32_e32 v24, v236
	v_mov_b32_e32 v25, v236
	v_mov_b32_e32 v86, 0
	v_mov_b32_e32 v87, v236
	v_mov_b32_e32 v88, v236
	v_mov_b32_e32 v89, v236
	v_mov_b32_e32 v184, 0
	v_mov_b32_e32 v185, v236
	s_waitcnt vmcnt(12)
	v_mul_f32_e32 v250, 0x3fb8aa3b, v250
	v_mul_f32_e32 v251, 0x3fb8aa3b, v251
	v_mul_f32_e32 v252, 0x3fb8aa3b, v252
	v_readlane_b32 s70, v254, 44
	v_cmp_gt_u32_e32 vcc, 4, v137
	s_nop 1
	v_lshl_add_u32 v253, v137, 2, s70
	ds_write_b32 v253, v250
	ds_write_b32 v253, v251 offset:2048
	s_and_saveexec_b64 s[70:71], vcc
	ds_write_b32 v253, v252 offset:4096
	s_or_b64 exec, exec, s[70:71]
	s_cmp_lg_u32 s88, 0
	s_cbranch_scc0 .Lsc_pr_sc
	s_mov_b32 s95, 0

.Lsc_nodec:
	ds_read_b128 v[98:101], v203 offset:8192
	ds_read_b128 v[102:105], v203 offset:8256
	ds_read_b128 v[110:113], v203 offset:25088
	ds_read_b128 v[130:133], v203 offset:33536
	s_mov_b64 s[38:39], -1
	s_waitcnt lgkmcnt(3)
	v_mfma_f32_16x16x32_bf16 v[106:109], v[98:101], v[26:29], 0
	s_cmp_lt_i32 s23, 6
	v_mfma_f32_16x16x32_bf16 v[98:101], v[98:101], v[34:37], 0
	s_waitcnt lgkmcnt(2)
	v_mfma_f32_16x16x32_bf16 v[126:129], v[102:105], v[30:33], v[106:109]
	s_nop 3
	ds_read_b128 v[106:109], v203 offset:16640
	v_mfma_f32_16x16x32_bf16 v[122:125], v[102:105], v[38:41], v[98:101]
	s_nop 2
	ds_read_b128 v[98:101], v203 offset:16704
	s_waitcnt lgkmcnt(1)
	v_mfma_f32_16x16x32_bf16 v[102:105], v[106:109], v[26:29], 0
	s_waitcnt lgkmcnt(0)
	v_mfma_f32_16x16x32_bf16 v[114:117], v[98:101], v[30:33], v[102:105]
	v_mfma_f32_16x16x32_bf16 v[102:105], v[106:109], v[34:37], 0
	v_mfma_f32_16x16x32_bf16 v[118:121], v[98:101], v[38:41], v[102:105]
	ds_read_b128 v[98:101], v203 offset:25152
	v_mfma_f32_16x16x32_bf16 v[102:105], v[110:113], v[26:29], 0
	s_waitcnt lgkmcnt(0)
	v_mfma_f32_16x16x32_bf16 v[106:109], v[98:101], v[30:33], v[102:105]
	v_mfma_f32_16x16x32_bf16 v[102:105], v[110:113], v[34:37], 0
	v_mfma_f32_16x16x32_bf16 v[110:113], v[98:101], v[38:41], v[102:105]
	s_nop 6
	ds_read_b128 v[102:105], v203 offset:33600
	v_mfma_f32_16x16x32_bf16 v[98:101], v[130:133], v[26:29], 0
	v_mfma_f32_16x16x32_bf16 v[130:133], v[130:133], v[34:37], 0
	s_waitcnt lgkmcnt(0)
	v_mfma_f32_16x16x32_bf16 v[98:101], v[102:105], v[30:33], v[98:101]
	v_mfma_f32_16x16x32_bf16 v[102:105], v[102:105], v[38:41], v[130:133]
	s_cbranch_scc0 .LBB0_96
	s_nop 3
	v_mov_b32_e32 v130, s16
	ds_read_b32 v136, v130 offset:1024
	s_waitcnt lgkmcnt(0)
	s_waitcnt lgkmcnt(14)
	v_pk_add_f32 v[126:127], v[126:127], v[136:137] op_sel_hi:[1,0]
	s_waitcnt lgkmcnt(2)
	v_pk_add_f32 v[214:215], v[128:129], v[136:137] op_sel_hi:[1,0]
	v_pk_add_f32 v[114:115], v[114:115], v[136:137] op_sel_hi:[1,0]
	v_pk_add_f32 v[142:143], v[110:111], v[136:137] op_sel_hi:[1,0]
	v_pk_add_f32 v[110:111], v[100:101], v[136:137] op_sel_hi:[1,0]
	v_pk_add_f32 v[100:101], v[102:103], v[136:137] op_sel_hi:[1,0]
	v_max3_f32 v102, v126, s10, v127
	v_max3_f32 v102, v102, v214, v215
	v_pk_add_f32 v[116:117], v[116:117], v[136:137] op_sel_hi:[1,0]
	v_max3_f32 v102, v102, v114, v115
	v_pk_add_f32 v[128:129], v[124:125], v[136:137] op_sel_hi:[1,0]
	v_pk_add_f32 v[134:135], v[118:119], v[136:137] op_sel_hi:[1,0]
	v_pk_add_f32 v[118:119], v[106:107], v[136:137] op_sel_hi:[1,0]
	v_max3_f32 v102, v102, v116, v117
	v_pk_add_f32 v[108:109], v[108:109], v[136:137] op_sel_hi:[1,0]
	v_max3_f32 v102, v102, v118, v119
	v_pk_add_f32 v[140:141], v[112:113], v[136:137] op_sel_hi:[1,0]
	v_pk_add_f32 v[112:113], v[98:99], v[136:137] op_sel_hi:[1,0]
	v_max3_f32 v102, v102, v108, v109
	v_max3_f32 v102, v102, v112, v113
	v_max3_f32 v102, v102, v110, v111
	v_mov_b32_e32 v103, v102
	s_nop 1
	v_permlane16_swap_b32_e32 v102, v103
	v_pk_add_f32 v[132:133], v[120:121], v[136:137] op_sel_hi:[1,0]
	v_pk_add_f32 v[130:131], v[122:123], v[136:137] op_sel_hi:[1,0]
	s_waitcnt lgkmcnt(0)
	v_pk_add_f32 v[98:99], v[104:105], v[136:137] op_sel_hi:[1,0]
	s_branch .Lmy_att_join

.Lmy_att_join:
	ds_read_b64_tr_b16 v[156:157], v197 offset:50432
	ds_read_b64_tr_b16 v[154:155], v197 offset:41984
	ds_read_b64_tr_b16 v[158:159], v197 offset:42016
	v_max_f32_e32 v102, v102, v103
	v_mov_b32_e32 v103, v102
	s_nop 1
	v_permlane32_swap_b32_e32 v102, v103
	v_max3_f32 v138, v181, v102, v103
	v_sub_f32_e32 v103, v126, v138
	v_exp_f32_e32 v107, v103
	v_sub_f32_e32 v103, v127, v138
	v_exp_f32_e32 v139, v103
	v_sub_f32_e32 v103, v214, v138
	v_exp_f32_e32 v144, v103
	v_sub_f32_e32 v103, v215, v138
	v_exp_f32_e32 v145, v103
	v_sub_f32_e32 v103, v114, v138
	v_exp_f32_e32 v146, v103
	v_sub_f32_e32 v103, v115, v138
	v_exp_f32_e32 v147, v103
	v_sub_f32_e32 v103, v116, v138
	v_sub_f32_e32 v102, v181, v138
	v_exp_f32_e32 v126, v103
	v_sub_f32_e32 v103, v117, v138
	v_exp_f32_e32 v124, v103
	v_sub_f32_e32 v103, v118, v138
	v_exp_f32_e32 v106, v102
	v_max3_f32 v102, v130, s10, v131
	v_exp_f32_e32 v122, v103
	v_sub_f32_e32 v103, v119, v138
	v_max3_f32 v102, v102, v128, v129
	v_exp_f32_e32 v120, v103
	v_sub_f32_e32 v103, v108, v138
	v_max3_f32 v102, v102, v134, v135
	v_exp_f32_e32 v118, v103
	v_sub_f32_e32 v103, v109, v138
	v_max3_f32 v102, v102, v132, v133
	v_exp_f32_e32 v116, v103
	v_sub_f32_e32 v103, v112, v138
	v_max3_f32 v102, v102, v142, v143
	v_exp_f32_e32 v114, v103
	v_sub_f32_e32 v103, v113, v138
	v_max3_f32 v102, v102, v140, v141
	v_exp_f32_e32 v112, v103
	v_sub_f32_e32 v103, v110, v138
	v_max3_f32 v102, v102, v100, v101
	v_exp_f32_e32 v110, v103
	v_sub_f32_e32 v103, v111, v138
	v_max3_f32 v102, v102, v98, v99
	v_exp_f32_e32 v108, v103
	v_mov_b32_e32 v103, v102
	s_nop 1
	v_permlane16_swap_b32_e32 v102, v103
	v_pk_mul_f32 v[88:89], v[88:89], v[106:107] op_sel_hi:[1,0]
	v_pk_mul_f32 v[86:87], v[86:87], v[106:107] op_sel_hi:[1,0]
	v_pk_mul_f32 v[92:93], v[92:93], v[106:107] op_sel_hi:[1,0]
	v_pk_mul_f32 v[90:91], v[90:91], v[106:107] op_sel_hi:[1,0]
	v_max_f32_e32 v102, v102, v103
	v_mov_b32_e32 v103, v102
	s_nop 1
	v_permlane32_swap_b32_e32 v102, v103
	v_pk_mul_f32 v[84:85], v[84:85], v[106:107] op_sel_hi:[1,0]
	v_pk_mul_f32 v[82:83], v[82:83], v[106:107] op_sel_hi:[1,0]
	v_pk_mul_f32 v[96:97], v[96:97], v[106:107] op_sel_hi:[1,0]
	v_pk_mul_f32 v[94:95], v[94:95], v[106:107] op_sel_hi:[1,0]
	v_max3_f32 v148, v175, v102, v103
	v_sub_f32_e32 v103, v130, v148
	v_exp_f32_e32 v149, v103
	v_sub_f32_e32 v103, v131, v148
	v_exp_f32_e32 v150, v103
	v_sub_f32_e32 v103, v128, v148
	v_exp_f32_e32 v151, v103
	v_sub_f32_e32 v103, v129, v148
	v_exp_f32_e32 v129, v103
	v_sub_f32_e32 v103, v134, v148
	v_exp_f32_e32 v152, v103
	v_sub_f32_e32 v103, v135, v148
	v_exp_f32_e32 v153, v103
	v_sub_f32_e32 v103, v132, v148
	v_sub_f32_e32 v102, v175, v148
	v_exp_f32_e32 v127, v103
	v_sub_f32_e32 v103, v133, v148
	v_exp_f32_e32 v125, v103
	v_sub_f32_e32 v103, v142, v148
	v_exp_f32_e32 v128, v102
	v_exp_f32_e32 v123, v103
	v_sub_f32_e32 v103, v143, v148
	v_exp_f32_e32 v121, v103
	v_sub_f32_e32 v103, v140, v148
	v_sub_f32_e32 v100, v100, v148
	v_sub_f32_e32 v98, v98, v148
	v_exp_f32_e32 v119, v103
	v_sub_f32_e32 v103, v141, v148
	v_exp_f32_e32 v115, v100
	v_sub_f32_e32 v100, v101, v148
	v_exp_f32_e32 v111, v98
	v_sub_f32_e32 v98, v99, v148
	v_exp_f32_e32 v117, v103
	v_exp_f32_e32 v113, v100
	v_exp_f32_e32 v109, v98
	v_pk_mul_f32 v[24:25], v[24:25], v[128:129] op_sel_hi:[1,0]
	v_pk_mul_f32 v[22:23], v[22:23], v[128:129] op_sel_hi:[1,0]
	v_cvt_pk_bf16_f32 v130, v107, v139
	v_cvt_pk_bf16_f32 v131, v144, v145
	v_cvt_pk_bf16_f32 v132, v146, v147
	v_cvt_pk_bf16_f32 v133, v126, v124
	v_cvt_pk_bf16_f32 v140, v149, v150
	v_cvt_pk_bf16_f32 v141, v151, v129
	v_cvt_pk_bf16_f32 v142, v152, v153
	v_cvt_pk_bf16_f32 v143, v127, v125
	s_waitcnt lgkmcnt(0)
	v_mfma_f32_16x16x32_bf16 v[86:89], v[154:157], v[130:133], v[86:89]
	v_mul_f32_e64 v104, v80, v128
	v_mul_f32_e64 v105, v81, v128
	v_pk_mul_f32 v[102:103], v[78:79], v[128:129] op_sel_hi:[1,0]
	v_cvt_pk_bf16_f32 v78, v122, v120
	v_mfma_f32_16x16x32_bf16 v[22:25], v[154:157], v[140:143], v[22:25]
	ds_read_b64_tr_b16 v[154:155], v197 offset:58880
	ds_read_b64_tr_b16 v[156:157], v199 offset:25344
	ds_read_b64_tr_b16 v[244:245], v199 offset:25376
	v_cvt_pk_bf16_f32 v79, v118, v116
	v_cvt_pk_bf16_f32 v80, v114, v112
	v_cvt_pk_bf16_f32 v81, v110, v108
	v_cvt_pk_bf16_f32 v98, v123, v121
	v_cvt_pk_bf16_f32 v99, v119, v117
	v_cvt_pk_bf16_f32 v100, v115, v113
	v_cvt_pk_bf16_f32 v101, v111, v109
	s_waitcnt lgkmcnt(1)
	v_mfma_f32_16x16x32_bf16 v[86:89], v[154:157], v[78:81], v[86:89]
	ds_read_b64_tr_b16 v[160:161], v197 offset:50464
	ds_read_b64_tr_b16 v[242:243], v197 offset:58912
	v_pk_mul_f32 v[44:45], v[44:45], v[128:129] op_sel_hi:[1,0]
	v_mfma_f32_16x16x32_bf16 v[22:25], v[154:157], v[98:101], v[22:25]
	ds_read_b64_tr_b16 v[154:155], v197 offset:42048
	ds_read_b64_tr_b16 v[156:157], v197 offset:50496
	v_pk_mul_f32 v[42:43], v[42:43], v[128:129] op_sel_hi:[1,0]
	v_pk_mul_f32 v[20:21], v[20:21], v[128:129] op_sel_hi:[1,0]
	s_waitcnt lgkmcnt(0)
	v_mfma_f32_16x16x32_bf16 v[90:93], v[154:157], v[130:133], v[90:93]
	v_mul_f32_e64 v18, v18, v128
	v_mul_f32_e64 v19, v19, v128
	v_mfma_f32_16x16x32_bf16 v[42:45], v[154:157], v[140:143], v[42:45]
	ds_read_b64_tr_b16 v[154:155], v197 offset:58944
	ds_read_b64_tr_b16 v[156:157], v199 offset:25408
	s_waitcnt lgkmcnt(0)
	v_mfma_f32_16x16x32_bf16 v[90:93], v[154:157], v[78:81], v[90:93]
	v_mfma_f32_16x16x32_bf16 v[42:45], v[154:157], v[98:101], v[42:45]
	ds_read_b64_tr_b16 v[154:155], v197 offset:42080
	ds_read_b64_tr_b16 v[156:157], v197 offset:50528
	v_mfma_f32_16x16x32_bf16 v[82:85], v[158:161], v[130:133], v[82:85]
	s_waitcnt lgkmcnt(0)
	v_mfma_f32_16x16x32_bf16 v[94:97], v[154:157], v[130:133], v[94:97]
	ds_read_b64_tr_b16 v[130:131], v197 offset:58976
	ds_read_b64_tr_b16 v[132:133], v199 offset:25440
	v_mfma_f32_16x16x32_bf16 v[18:21], v[158:161], v[140:143], v[18:21]
	v_mfma_f32_16x16x32_bf16 v[102:105], v[154:157], v[140:143], v[102:105]
	v_mfma_f32_16x16x32_bf16 v[82:85], v[242:245], v[78:81], v[82:85]
	v_mfma_f32_16x16x32_bf16 v[18:21], v[242:245], v[98:101], v[18:21]
	s_waitcnt lgkmcnt(0)
	v_mfma_f32_16x16x32_bf16 v[94:97], v[130:133], v[78:81], v[94:97]
	v_mfma_f32_16x16x32_bf16 v[78:81], v[130:133], v[98:101], v[102:105]
	s_cmp_lg_u32 s88, 0
	s_cbranch_scc1 .Lsc_noscan
	s_waitcnt vmcnt(0)
	s_cmp_ge_u32 s89, 8
	s_cbranch_scc1 .Lsc_noscan
	s_and_b32 s70, s89, 1
	s_lshl_b32 s70, s70, 12
	v_add_u32_e32 v247, s70, v246
	ds_read_b32 v2, v247
	ds_read_b32 v3, v247 offset:256
	ds_read_b32 v4, v247 offset:512
	ds_read_b32 v5, v247 offset:768
	ds_read_b32 v6, v247 offset:1024
	ds_read_b32 v7, v247 offset:1280
	ds_read_b32 v8, v247 offset:1536
	ds_read_b32 v9, v247 offset:1792
	ds_read_b32 v10, v247 offset:2048
	ds_read_b32 v11, v247 offset:2304
	ds_read_b32 v12, v247 offset:2560
	ds_read_b32 v13, v247 offset:2816
	ds_read_b32 v14, v247 offset:3072
	ds_read_b32 v15, v247 offset:3328
	ds_read_b32 v16, v247 offset:3584
	ds_read_b32 v17, v247 offset:3840
	s_lshl_b32 s70, s89, 21
	s_mov_b32 s71, 0
	v_lshl_add_u64 v[98:99], s[70:71], 0, v[166:167]
	s_mov_b32 s100, 0x20000
	s_mov_b32 s101, 0
	s_waitcnt lgkmcnt(0)
	v_readlane_b32 s70, v241, 0
	v_cvt_pk_bf16_f32 v100, v177, v176
	global_store_dword v[98:99], v100, off
	v_lshlrev_b32_e32 v101, 16, v2
	v_and_b32_e32 v102, 0xffff0000, v2
	v_readlane_b32 s71, v241, 1
	v_fma_f32 v177, v177, s70, v101
	v_fma_f32 v176, v176, s70, v102
	v_lshl_add_u64 v[98:99], v[98:99], 0, s[100:101]
	v_cvt_pk_bf16_f32 v100, v177, v176
	global_store_dword v[98:99], v100, off
	v_lshlrev_b32_e32 v101, 16, v3
	v_and_b32_e32 v102, 0xffff0000, v3
	v_readlane_b32 s70, v241, 2
	v_fma_f32 v177, v177, s71, v101
	v_fma_f32 v176, v176, s71, v102
	v_lshl_add_u64 v[98:99], v[98:99], 0, s[100:101]
	v_cvt_pk_bf16_f32 v100, v177, v176
	global_store_dword v[98:99], v100, off
	v_lshlrev_b32_e32 v101, 16, v4
	v_and_b32_e32 v102, 0xffff0000, v4
	v_readlane_b32 s71, v241, 3
	v_fma_f32 v177, v177, s70, v101
	v_fma_f32 v176, v176, s70, v102
	v_lshl_add_u64 v[98:99], v[98:99], 0, s[100:101]
	v_cvt_pk_bf16_f32 v100, v177, v176
	global_store_dword v[98:99], v100, off
	v_lshlrev_b32_e32 v101, 16, v5
	v_and_b32_e32 v102, 0xffff0000, v5
	v_readlane_b32 s70, v241, 4
	v_fma_f32 v177, v177, s71, v101
	v_fma_f32 v176, v176, s71, v102
	v_lshl_add_u64 v[98:99], v[98:99], 0, s[100:101]
	v_cvt_pk_bf16_f32 v100, v177, v176
	global_store_dword v[98:99], v100, off
	v_lshlrev_b32_e32 v101, 16, v6
	v_and_b32_e32 v102, 0xffff0000, v6
	v_readlane_b32 s71, v241, 5
	v_fma_f32 v177, v177, s70, v101
	v_fma_f32 v176, v176, s70, v102
	v_lshl_add_u64 v[98:99], v[98:99], 0, s[100:101]
	v_cvt_pk_bf16_f32 v100, v177, v176
	global_store_dword v[98:99], v100, off
	v_lshlrev_b32_e32 v101, 16, v7
	v_and_b32_e32 v102, 0xffff0000, v7
	v_readlane_b32 s70, v241, 6
	v_fma_f32 v177, v177, s71, v101
	v_fma_f32 v176, v176, s71, v102
	v_lshl_add_u64 v[98:99], v[98:99], 0, s[100:101]
	v_cvt_pk_bf16_f32 v100, v177, v176
	global_store_dword v[98:99], v100, off
	v_lshlrev_b32_e32 v101, 16, v8
	v_and_b32_e32 v102, 0xffff0000, v8
	v_readlane_b32 s71, v241, 7
	v_fma_f32 v177, v177, s70, v101
	v_fma_f32 v176, v176, s70, v102
	v_lshl_add_u64 v[98:99], v[98:99], 0, s[100:101]
	v_cvt_pk_bf16_f32 v100, v177, v176
	global_store_dword v[98:99], v100, off
	v_lshlrev_b32_e32 v101, 16, v9
	v_and_b32_e32 v102, 0xffff0000, v9
	v_readlane_b32 s70, v241, 8
	v_fma_f32 v177, v177, s71, v101
	v_fma_f32 v176, v176, s71, v102
	v_lshl_add_u64 v[98:99], v[98:99], 0, s[100:101]
	v_cvt_pk_bf16_f32 v100, v177, v176
	global_store_dword v[98:99], v100, off
	v_lshlrev_b32_e32 v101, 16, v10
	v_and_b32_e32 v102, 0xffff0000, v10
	v_readlane_b32 s71, v241, 9
	v_fma_f32 v177, v177, s70, v101
	v_fma_f32 v176, v176, s70, v102
	v_lshl_add_u64 v[98:99], v[98:99], 0, s[100:101]
	v_cvt_pk_bf16_f32 v100, v177, v176
	global_store_dword v[98:99], v100, off
	v_lshlrev_b32_e32 v101, 16, v11
	v_and_b32_e32 v102, 0xffff0000, v11
	v_readlane_b32 s70, v241, 10
	v_fma_f32 v177, v177, s71, v101
	v_fma_f32 v176, v176, s71, v102
	v_lshl_add_u64 v[98:99], v[98:99], 0, s[100:101]
	v_cvt_pk_bf16_f32 v100, v177, v176
	global_store_dword v[98:99], v100, off
	v_lshlrev_b32_e32 v101, 16, v12
	v_and_b32_e32 v102, 0xffff0000, v12
	v_readlane_b32 s71, v241, 11
	v_fma_f32 v177, v177, s70, v101
	v_fma_f32 v176, v176, s70, v102
	v_lshl_add_u64 v[98:99], v[98:99], 0, s[100:101]
	v_cvt_pk_bf16_f32 v100, v177, v176
	global_store_dword v[98:99], v100, off
	v_lshlrev_b32_e32 v101, 16, v13
	v_and_b32_e32 v102, 0xffff0000, v13
	v_readlane_b32 s70, v241, 12
	v_fma_f32 v177, v177, s71, v101
	v_fma_f32 v176, v176, s71, v102
	v_lshl_add_u64 v[98:99], v[98:99], 0, s[100:101]
	v_cvt_pk_bf16_f32 v100, v177, v176
	global_store_dword v[98:99], v100, off
	v_lshlrev_b32_e32 v101, 16, v14
	v_and_b32_e32 v102, 0xffff0000, v14
	v_readlane_b32 s71, v241, 13
	v_fma_f32 v177, v177, s70, v101
	v_fma_f32 v176, v176, s70, v102
	v_lshl_add_u64 v[98:99], v[98:99], 0, s[100:101]
	v_cvt_pk_bf16_f32 v100, v177, v176
	global_store_dword v[98:99], v100, off
	v_lshlrev_b32_e32 v101, 16, v15
	v_and_b32_e32 v102, 0xffff0000, v15
	v_readlane_b32 s70, v241, 14
	v_fma_f32 v177, v177, s71, v101
	v_fma_f32 v176, v176, s71, v102
	v_lshl_add_u64 v[98:99], v[98:99], 0, s[100:101]
	v_cvt_pk_bf16_f32 v100, v177, v176
	global_store_dword v[98:99], v100, off
	v_lshlrev_b32_e32 v101, 16, v16
	v_and_b32_e32 v102, 0xffff0000, v16
	v_readlane_b32 s71, v241, 15
	v_fma_f32 v177, v177, s70, v101
	v_fma_f32 v176, v176, s70, v102
	v_lshl_add_u64 v[98:99], v[98:99], 0, s[100:101]
	v_cvt_pk_bf16_f32 v100, v177, v176
	global_store_dword v[98:99], v100, off
	v_lshlrev_b32_e32 v101, 16, v17
	v_and_b32_e32 v102, 0xffff0000, v17
	v_fma_f32 v177, v177, s71, v101
	v_fma_f32 v176, v176, s71, v102

.LBB0_342:
	v_mov_b32_e32 v24, v164
	s_and_b32 s17, s36, 0x7f
	v_readfirstlane_b32 s16, v24
	s_ashr_i32 s28, s16, 6
	s_lshl_b32 s67, s36, 6
	s_mov_b64 s[24:25], s[52:53]
	s_add_u32 s30, s24, s60
	s_addc_u32 s31, s25, s61
	s_mov_b64 s[24:25], s[54:55]
	v_and_b32_e32 v25, 63, v24
	s_add_u32 s24, s24, s62
	v_or_b32_e32 v0, s67, v25
	s_addc_u32 s25, s25, s63
	s_add_i32 s26, s28, s15
	v_ashrrev_i32_e32 v1, 31, v0
	s_ashr_i32 s27, s26, 31
	v_lshlrev_b64 v[0:1], 5, v[0:1]
	s_ashr_i32 s29, s28, 31
	s_lshl_b64 s[26:27], s[26:27], 2
	v_lshl_add_u64 v[0:1], s[22:23], 0, v[0:1]
	s_add_u32 s34, s56, s26
	v_lshl_add_u64 v[0:1], s[28:29], 2, v[0:1]
	s_addc_u32 s35, s57, s27
	global_load_dword v0, v[0:1], off
	s_nop 0
	global_load_dword v1, v163, s[34:35]
	s_add_u32 s34, s58, s26
	s_addc_u32 s35, s59, s27
	global_load_dword v2, v163, s[34:35]
	s_mov_b32 s0, 0xb2a5705f
	v_lshlrev_b32_e32 v128, 2, v25
	v_cmp_gt_u32_e64 s[40:41], 16, v25
	v_xor_b32_e32 v119, 0x80, v128
	s_cmp_eq_u32 s17, 0
	s_waitcnt vmcnt(0)
	v_add_f32_e32 v0, v0, v1
	v_mul_f32_e64 v1, |v0|, s48
	v_fma_f32 v4, |v0|, s48, -v1
	v_rndne_f32_e32 v5, v1
	v_fma_f32 v4, |v0|, s0, v4
	v_sub_f32_e32 v1, v1, v5
	s_waitcnt vmcnt(0)
	v_mov_b32_e32 v206, s36
	v_lshl_add_u32 v206, v206, 3, s28
	v_lshlrev_b32_e32 v206, 14, v206
	v_and_b32_e32 v207, 48, v25
	v_add_u32_e32 v206, v206, v207
	v_and_b32_e32 v207, 15, v24
	v_lshl_add_u32 v206, v207, 8, v206
	v_mov_b32_e32 v207, 0
	s_mov_b32 s100, s37
	s_mov_b32 s101, s38
	v_lshl_add_u64 v[206:207], s[100:101], 0, v[206:207]
	s_mov_b32 s100, 0x1000
	s_mov_b32 s101, 0
	global_load_dwordx4 v[166:169], v[206:207], off sc1
	global_load_dwordx4 v[182:185], v[206:207], off offset:64 sc1
	global_load_dwordx4 v[198:201], v[206:207], off offset:128 sc1
	global_load_dwordx4 v[238:241], v[206:207], off offset:192 sc1
	v_lshl_add_u64 v[206:207], v[206:207], 0, s[100:101]
	global_load_dwordx4 v[170:173], v[206:207], off sc1
	global_load_dwordx4 v[186:189], v[206:207], off offset:64 sc1
	global_load_dwordx4 v[202:205], v[206:207], off offset:128 sc1
	global_load_dwordx4 v[242:245], v[206:207], off offset:192 sc1
	v_lshl_add_u64 v[206:207], v[206:207], 0, s[100:101]
	global_load_dwordx4 v[174:177], v[206:207], off sc1
	global_load_dwordx4 v[190:193], v[206:207], off offset:64 sc1
	global_load_dwordx4 v[230:233], v[206:207], off offset:128 sc1
	global_load_dwordx4 v[246:249], v[206:207], off offset:192 sc1
	v_lshl_add_u64 v[206:207], v[206:207], 0, s[100:101]
	global_load_dwordx4 v[178:181], v[206:207], off sc1
	global_load_dwordx4 v[194:197], v[206:207], off offset:64 sc1
	global_load_dwordx4 v[234:237], v[206:207], off offset:128 sc1
	global_load_dwordx4 v[250:253], v[206:207], off offset:192 sc1
	v_mul_f32_e32 v6, 0x3fb8aa3b, v2
	v_add_f32_e32 v1, v1, v4
	v_cvt_i32_f32_e32 v5, v5
	v_fma_f32 v7, v2, s4, -v6
	v_rndne_f32_e32 v8, v6
	v_exp_f32_e32 v1, v1
	v_fmac_f32_e32 v7, 0x32a5705f, v2
	v_sub_f32_e32 v4, v6, v8
	v_add_f32_e32 v4, v4, v7
	v_cvt_i32_f32_e32 v6, v8
	v_exp_f32_e32 v4, v4
	s_mov_b32 s0, 0x42ce8ed0
	v_ldexp_f32 v1, v1, v5
	v_cmp_ngt_f32_e64 vcc, |v0|, s0
	s_mov_b32 s0, 0xc2b17218
	v_ldexp_f32 v4, v4, v6
	v_cndmask_b32_e32 v1, 0, v1, vcc
	v_cmp_nlt_f32_e64 vcc, |v0|, s0
	v_max_f32_e32 v3, 0, v0
	s_mov_b32 s0, 0x3f2aaaab
	v_cndmask_b32_e32 v5, v220, v1, vcc
	v_add_f32_e32 v6, 1.0, v5
	v_cmp_ngt_f32_e32 vcc, s82, v2
	v_add_f32_e32 v7, -1.0, v6
	v_frexp_mant_f32_e32 v8, v6
	v_cvt_f64_f32_e32 v[0:1], v6
	v_cndmask_b32_e32 v4, 0, v4, vcc
	v_sub_f32_e32 v9, v7, v6
	v_frexp_exp_i32_f64_e32 v0, v[0:1]
	v_cmp_gt_f32_e32 vcc, s0, v8
	v_sub_f32_e32 v7, v5, v7
	v_add_f32_e32 v1, 1.0, v9
	v_subbrev_co_u32_e32 v0, vcc, 0, v0, vcc
	v_add_f32_e32 v1, v7, v1
	v_sub_u32_e32 v7, 0, v0
	v_cvt_f32_i32_e32 v0, v0
	v_ldexp_f32 v6, v6, v7
	v_ldexp_f32 v1, v1, v7
	v_add_f32_e32 v7, -1.0, v6
	v_add_f32_e32 v8, 1.0, v6
	v_add_f32_e32 v9, 1.0, v7
	v_add_f32_e32 v10, -1.0, v8
	v_sub_f32_e32 v9, v6, v9
	v_sub_f32_e32 v6, v6, v10
	v_mul_f32_e32 v10, 0x3f317218, v0
	v_add_f32_e32 v9, v1, v9
	v_add_f32_e32 v1, v1, v6
	s_mov_b32 s0, 0x3f317218
	v_fma_f32 v6, v0, s0, -v10
	v_add_f32_e32 v11, v7, v9
	v_add_f32_e32 v12, v8, v1
	v_fmac_f32_e32 v6, 0xb102e308, v0
	v_sub_f32_e32 v0, v7, v11
	v_sub_f32_e32 v7, v8, v12
	v_rcp_f32_e32 v8, v12
	v_add_f32_e32 v13, v10, v6
	v_add_f32_e32 v1, v1, v7
	v_sub_f32_e32 v7, v13, v10
	v_sub_f32_e32 v6, v6, v7
	v_mul_f32_e32 v7, v11, v8
	v_add_f32_e32 v0, v9, v0
	v_mul_f32_e32 v9, v12, v7
	v_fma_f32 v10, v7, v12, -v9
	v_fmac_f32_e32 v10, v7, v1
	v_add_f32_e32 v14, v9, v10
	v_sub_f32_e32 v15, v11, v14
	v_sub_f32_e32 v9, v14, v9
	v_sub_f32_e32 v11, v11, v15
	v_sub_f32_e32 v9, v9, v10
	v_sub_f32_e32 v10, v11, v14
	v_add_f32_e32 v0, v0, v10
	v_add_f32_e32 v0, v9, v0
	v_add_f32_e32 v9, v15, v0
	v_mul_f32_e32 v10, v8, v9
	v_sub_f32_e32 v11, v15, v9
	v_mul_f32_e32 v14, v12, v10
	v_add_f32_e32 v0, v0, v11
	v_add_f32_e32 v11, v7, v10
	v_fma_f32 v12, v10, v12, -v14
	v_sub_f32_e32 v7, v11, v7
	v_fmac_f32_e32 v12, v10, v1
	v_sub_f32_e32 v1, v10, v7
	v_add_f32_e32 v7, v14, v12
	v_sub_f32_e32 v10, v7, v14
	v_sub_f32_e32 v14, v9, v7
	v_sub_f32_e32 v9, v9, v14
	v_sub_f32_e32 v7, v9, v7
	v_sub_f32_e32 v10, v10, v12
	v_add_f32_e32 v0, v0, v7
	v_add_f32_e32 v0, v10, v0
	v_add_f32_e32 v0, v14, v0
	v_mul_f32_e32 v0, v8, v0
	v_add_f32_e32 v0, v1, v0
	v_add_f32_e32 v1, v11, v0
	v_mul_f32_e32 v7, v1, v1
	v_fmamk_f32 v10, v7, 0x3e9b6dac, v208
	v_sub_f32_e32 v8, v1, v11
	v_ldexp_f32 v9, v1, 1
	v_mul_f32_e32 v1, v1, v7
	v_fmaak_f32 v7, v7, v10, 0x3f2aaada
	v_mul_f32_e32 v1, v1, v7
	v_add_f32_e32 v7, v9, v1
	v_sub_f32_e32 v0, v0, v8
	v_sub_f32_e32 v8, v7, v9
	v_ldexp_f32 v0, v0, 1
	v_sub_f32_e32 v1, v1, v8
	v_add_f32_e32 v0, v0, v1
	v_add_f32_e32 v1, v7, v0
	v_sub_f32_e32 v7, v1, v7
	v_add_f32_e32 v8, v13, v1
	v_sub_f32_e32 v0, v0, v7
	v_sub_f32_e32 v7, v8, v13
	v_sub_f32_e32 v9, v8, v7
	v_sub_f32_e32 v1, v1, v7
	v_add_f32_e32 v7, v6, v0
	v_sub_f32_e32 v9, v13, v9
	v_sub_f32_e32 v10, v7, v6
	v_add_f32_e32 v1, v1, v9
	v_sub_f32_e32 v9, v7, v10
	v_sub_f32_e32 v0, v0, v10
	v_sub_f32_e32 v6, v6, v9
	v_add_f32_e32 v1, v7, v1
	v_add_f32_e32 v0, v0, v6
	v_add_f32_e32 v6, v8, v1
	v_sub_f32_e32 v7, v6, v8
	v_sub_f32_e32 v1, v1, v7
	v_add_f32_e32 v0, v0, v1
	s_mov_b32 s0, 0x7f800000
	v_add_f32_e32 v0, v6, v0
	v_cmp_neq_f32_e32 vcc, s0, v5
	s_mov_b32 s0, 0x33800000
	v_lshlrev_b32_e32 v10, 1, v24
	v_cndmask_b32_e32 v0, v220, v0, vcc
	v_cmp_lt_f32_e64 vcc, |v5|, s0
	s_movk_i32 s0, 0xffc0
	v_ashrrev_i32_e32 v11, 31, v10
	v_cndmask_b32_e32 v0, v0, v5, vcc
	v_cmp_nlt_f32_e32 vcc, s49, v2
	v_add_f32_e32 v0, v3, v0
	v_add_u32_e32 v3, 0xfc, v128
	v_cndmask_b32_e32 v1, v220, v4, vcc
	v_mul_f32_e64 v2, v0, -v1
	v_and_b32_e32 v3, 0xfc, v3
	ds_bpermute_b32 v3, v3, v2
	v_cmp_eq_u32_e32 vcc, 0, v25
	v_lshlrev_b64 v[8:9], 2, v[10:11]
	s_waitcnt lgkmcnt(0)
	v_fma_f32 v1, v0, -v1, v3
	v_cndmask_b32_e32 v1, v1, v2, vcc
	v_add_u32_e32 v2, 0xf8, v128
	v_and_b32_e32 v2, 0xfc, v2
	ds_bpermute_b32 v2, v2, v1
	v_cmp_gt_u32_e32 vcc, 2, v25
	v_add_u32_e32 v3, 0xc0, v128
	s_waitcnt lgkmcnt(0)
	v_add_f32_e32 v2, v1, v2
	v_cndmask_b32_e32 v1, v2, v1, vcc
	v_add_u32_e32 v2, 0xf0, v128
	v_and_b32_e32 v2, 0xfc, v2
	ds_bpermute_b32 v2, v2, v1
	v_cmp_gt_u32_e32 vcc, 4, v25
	s_waitcnt lgkmcnt(0)
	v_add_f32_e32 v2, v1, v2
	v_cndmask_b32_e32 v1, v2, v1, vcc
	v_add_u32_e32 v2, 0xe0, v128
	v_and_b32_e32 v2, 0xfc, v2
	ds_bpermute_b32 v2, v2, v1
	v_cmp_gt_u32_e32 vcc, 8, v25
	s_waitcnt lgkmcnt(0)
	v_add_f32_e32 v2, v1, v2
	v_cndmask_b32_e32 v1, v2, v1, vcc
	v_and_b32_e32 v2, 0xfc, v3
	ds_bpermute_b32 v2, v2, v1
	v_mov_b32_e32 v3, s16
	v_bfi_b32 v3, s0, v3, v24
	v_cmp_gt_u32_e32 vcc, 32, v25
	v_lshl_add_u32 v3, v3, 2, 0
	s_waitcnt lgkmcnt(0)
	v_add_f32_e32 v2, v1, v2
	v_cndmask_b32_e64 v1, v2, v1, s[40:41]
	ds_bpermute_b32 v2, v119, v1
	s_waitcnt lgkmcnt(0)
	v_add_f32_e32 v2, v1, v2
	v_cndmask_b32_e32 v1, v2, v1, vcc
	ds_write2st64_b32 v3, v0, v1 offset1:8
	v_lshl_add_u64 v[0:1], s[30:31], 0, v[8:9]
	v_add_co_u32_e32 v2, vcc, 0x1000, v0
	v_lshl_add_u64 v[8:9], s[24:25], 0, v[8:9]
	s_nop 0
	v_addc_co_u32_e32 v3, vcc, 0, v1, vcc
	v_add_co_u32_e32 v4, vcc, 0x2000, v0
	s_nop 1
	v_addc_co_u32_e32 v5, vcc, 0, v1, vcc
	v_add_co_u32_e32 v6, vcc, 0x3000, v0
	s_nop 1
	v_addc_co_u32_e32 v7, vcc, 0, v1, vcc
	flat_load_dwordx2 v[0:1], v[0:1]
	s_nop 0
	flat_load_dwordx2 v[2:3], v[2:3]
	s_nop 0
	flat_load_dwordx2 v[4:5], v[4:5]
	s_nop 0
	flat_load_dwordx2 v[6:7], v[6:7]
	s_nop 0
	flat_load_dwordx2 v[8:9], v[8:9]
	s_mul_i32 s100, s51, 0x1600
	s_mul_hi_i32 s101, s51, 0x1600
	v_lshl_add_u64 v[132:133], v[10:11], 1, s[100:101]
	s_mov_b32 s100, s39
	s_mov_b32 s101, s50
	v_lshl_add_u64 v[132:133], v[132:133], 0, s[100:101]
	s_mov_b32 s100, 0xfffeb600
	s_mov_b32 s101, -1
	v_lshl_add_u64 v[132:133], v[132:133], 0, s[100:101]
	s_mov_b32 s100, 0x1600
	s_mov_b32 s101, 0
	global_load_dword v142, v[132:133], off
	v_lshl_add_u64 v[132:133], v[132:133], 0, s[100:101]
	global_load_dword v143, v[132:133], off
	v_lshl_add_u64 v[132:133], v[132:133], 0, s[100:101]
	global_load_dword v144, v[132:133], off
	v_lshl_add_u64 v[132:133], v[132:133], 0, s[100:101]
	global_load_dword v145, v[132:133], off
	v_lshl_add_u64 v[132:133], v[132:133], 0, s[100:101]
	global_load_dword v146, v[132:133], off
	v_lshl_add_u64 v[132:133], v[132:133], 0, s[100:101]
	global_load_dword v147, v[132:133], off
	v_lshl_add_u64 v[132:133], v[132:133], 0, s[100:101]
	global_load_dword v148, v[132:133], off
	v_lshl_add_u64 v[132:133], v[132:133], 0, s[100:101]
	global_load_dword v149, v[132:133], off
	v_lshl_add_u64 v[132:133], v[132:133], 0, s[100:101]
	global_load_dword v151, v[132:133], off
	v_lshl_add_u64 v[132:133], v[132:133], 0, s[100:101]
	global_load_dword v152, v[132:133], off
	v_lshl_add_u64 v[132:133], v[132:133], 0, s[100:101]
	global_load_dword v153, v[132:133], off
	v_lshl_add_u64 v[132:133], v[132:133], 0, s[100:101]
	global_load_dword v154, v[132:133], off
	v_lshl_add_u64 v[132:133], v[132:133], 0, s[100:101]
	global_load_dword v155, v[132:133], off
	v_lshl_add_u64 v[132:133], v[132:133], 0, s[100:101]
	global_load_dword v156, v[132:133], off
	v_lshl_add_u64 v[132:133], v[132:133], 0, s[100:101]
	global_load_dword v157, v[132:133], off
	v_lshl_add_u64 v[132:133], v[132:133], 0, s[100:101]
	global_load_dword v158, v[132:133], off
	s_cbranch_scc1 .LBB0_344
	s_mul_i32 s24, s67, 0x1600
	s_mul_hi_i32 s17, s67, 0x1600
	s_add_u32 s24, s20, s24
	s_addc_u32 s25, s21, s17
	v_lshl_add_u64 v[12:13], v[10:11], 1, s[24:25]
	v_add_co_u32_e32 v14, vcc, 0xffffd000, v12
	s_nop 1
	v_addc_co_u32_e32 v15, vcc, -1, v13, vcc
	global_load_dword v16, v[14:15], off offset:-2048
	v_add_co_u32_e32 v14, vcc, 0xffffe000, v12
	s_nop 1
	v_addc_co_u32_e32 v15, vcc, -1, v13, vcc
	global_load_dword v14, v[14:15], off offset:-512
	s_nop 0
	global_load_dword v15, v[12:13], off offset:-3072
	s_waitcnt vmcnt(0)
	v_lshlrev_b32_e32 v12, 16, v16
	v_and_b32_e32 v13, 0xffff0000, v16
	v_lshlrev_b32_e32 v16, 16, v14
	v_and_b32_e32 v17, 0xffff0000, v14
	v_lshlrev_b32_e32 v14, 16, v15
	v_and_b32_e32 v15, 0xffff0000, v15
	s_branch .LBB0_345

.LBB0_394:
	s_or_b64 exec, exec, s[26:27]
	s_lshl_b32 s25, s38, 6
	s_sub_i32 s25, s25, 30
	s_and_b32 s0, s38, 0x7f
	s_cmp_eq_u32 s0, 0
	s_cselect_b32 s0, 30, 0
	v_and_b32_e32 v108, 31, v164
	v_lshlrev_b32_e32 v108, 4, v108
	v_mov_b32_e32 v109, 0
	s_add_u32 s26, s44, 0x1200
	s_addc_u32 s27, s45, 0
	v_lshl_add_u64 v[108:109], s[26:27], 0, v[108:109]
	v_mov_b32_e32 v110, v164
	v_ashrrev_i32_e32 v111, 5, v110
	v_cmp_gt_u32_e32 vcc, 0xbc0, v110
	v_cmp_le_i32_e64 s[100:101], s0, v111
	s_and_b64 vcc, vcc, s[100:101]
	s_and_saveexec_b64 s[100:101], vcc
	v_add_u32_e32 v111, s25, v111
	v_mad_i64_i32 v[112:113], vcc, v111, s76, v[108:109]
	global_load_dwordx4 v[60:63], v[112:113], off
	global_load_dwordx4 v[64:67], v[112:113], off offset:512
	s_mov_b64 exec, s[100:101]
	v_add_u32_e32 v110, 0x200, v164
	v_ashrrev_i32_e32 v111, 5, v110
	v_cmp_gt_u32_e32 vcc, 0xbc0, v110
	v_cmp_le_i32_e64 s[100:101], s0, v111
	s_and_b64 vcc, vcc, s[100:101]
	s_and_saveexec_b64 s[100:101], vcc
	v_add_u32_e32 v111, s25, v111
	v_mad_i64_i32 v[112:113], vcc, v111, s76, v[108:109]
	global_load_dwordx4 v[68:71], v[112:113], off
	global_load_dwordx4 v[72:75], v[112:113], off offset:512
	s_mov_b64 exec, s[100:101]
	v_add_u32_e32 v110, 0x400, v164
	v_ashrrev_i32_e32 v111, 5, v110
	v_cmp_gt_u32_e32 vcc, 0xbc0, v110
	v_cmp_le_i32_e64 s[100:101], s0, v111
	s_and_b64 vcc, vcc, s[100:101]
	s_and_saveexec_b64 s[100:101], vcc
	v_add_u32_e32 v111, s25, v111
	v_mad_i64_i32 v[112:113], vcc, v111, s76, v[108:109]
	global_load_dwordx4 v[76:79], v[112:113], off
	global_load_dwordx4 v[80:83], v[112:113], off offset:512
	s_mov_b64 exec, s[100:101]
	v_add_u32_e32 v110, 0x600, v164
	v_ashrrev_i32_e32 v111, 5, v110
	v_cmp_gt_u32_e32 vcc, 0xbc0, v110
	v_cmp_le_i32_e64 s[100:101], s0, v111
	s_and_b64 vcc, vcc, s[100:101]
	s_and_saveexec_b64 s[100:101], vcc
	v_add_u32_e32 v111, s25, v111
	v_mad_i64_i32 v[112:113], vcc, v111, s76, v[108:109]
	global_load_dwordx4 v[84:87], v[112:113], off
	global_load_dwordx4 v[88:91], v[112:113], off offset:512
	s_mov_b64 exec, s[100:101]
	v_add_u32_e32 v110, 0x800, v164
	v_ashrrev_i32_e32 v111, 5, v110
	v_cmp_gt_u32_e32 vcc, 0xbc0, v110
	v_cmp_le_i32_e64 s[100:101], s0, v111
	s_and_b64 vcc, vcc, s[100:101]
	s_and_saveexec_b64 s[100:101], vcc
	v_add_u32_e32 v111, s25, v111
	v_mad_i64_i32 v[112:113], vcc, v111, s76, v[108:109]
	global_load_dwordx4 v[92:95], v[112:113], off
	global_load_dwordx4 v[96:99], v[112:113], off offset:512
	s_mov_b64 exec, s[100:101]
	v_add_u32_e32 v110, 0xa00, v164
	v_ashrrev_i32_e32 v111, 5, v110
	v_cmp_gt_u32_e32 vcc, 0xbc0, v110
	v_cmp_le_i32_e64 s[100:101], s0, v111
	s_and_b64 vcc, vcc, s[100:101]
	s_and_saveexec_b64 s[100:101], vcc
	v_add_u32_e32 v111, s25, v111
	v_mad_i64_i32 v[112:113], vcc, v111, s76, v[108:109]
	global_load_dwordx4 v[100:103], v[112:113], off
	global_load_dwordx4 v[104:107], v[112:113], off offset:512
	s_mov_b64 exec, s[100:101]
	s_and_b32 s25, s38, 0x7f
	s_cmp_eq_u32 s25, 0
	s_cselect_b64 s[26:27], -1, 0
	s_cmp_lg_u32 s25, 0
	s_movk_i32 s0, 0x180
	s_cselect_b64 s[36:37], -1, 0
	v_cmp_gt_i32_e32 vcc, s0, v37
	s_waitcnt lgkmcnt(0)
	s_barrier
	s_and_saveexec_b64 s[28:29], vcc
	s_cbranch_execz .LBB0_416
	s_add_u32 s34, s34, s22
	s_addc_u32 s35, s35, s23
	v_lshlrev_b32_e32 v10, 1, v37
	s_add_u32 s30, s30, s18
	v_ashrrev_i32_e32 v11, 31, v10
	s_addc_u32 s31, s31, s19
	v_lshlrev_b64 v[8:9], 2, v[10:11]
	v_lshl_add_u64 v[0:1], s[30:31], 0, v[8:9]
	v_add_co_u32_e32 v2, vcc, s1, v0
	v_lshl_add_u64 v[8:9], s[34:35], 0, v[8:9]
	s_nop 0
	v_addc_co_u32_e32 v3, vcc, 0, v1, vcc
	v_add_co_u32_e32 v4, vcc, 0x2000, v0
	s_nop 1
	v_addc_co_u32_e32 v5, vcc, 0, v1, vcc
	v_add_co_u32_e32 v6, vcc, 0x3000, v0
	s_nop 1
	v_addc_co_u32_e32 v7, vcc, 0, v1, vcc
	flat_load_dwordx2 v[0:1], v[0:1]
	s_nop 0
	flat_load_dwordx2 v[2:3], v[2:3]
	s_nop 0
	flat_load_dwordx2 v[4:5], v[4:5]
	s_nop 0
	flat_load_dwordx2 v[6:7], v[6:7]
	s_andn2_b64 vcc, exec, s[36:37]
	flat_load_dwordx2 v[8:9], v[8:9]
	s_mul_i32 s100, s71, 0x1600
	s_mul_hi_i32 s101, s71, 0x1600
	v_lshl_add_u64 v[114:115], v[10:11], 1, s[100:101]
	s_mov_b32 s100, s15
	s_mov_b32 s101, s70
	v_lshl_add_u64 v[114:115], v[114:115], 0, s[100:101]
	s_mov_b32 s100, 0xfffeb600
	s_mov_b32 s101, -1
	v_lshl_add_u64 v[114:115], v[114:115], 0, s[100:101]
	s_mov_b32 s100, 0x1600
	s_mov_b32 s101, 0
	global_load_dword v44, v[114:115], off
	v_lshl_add_u64 v[114:115], v[114:115], 0, s[100:101]
	global_load_dword v45, v[114:115], off
	v_lshl_add_u64 v[114:115], v[114:115], 0, s[100:101]
	global_load_dword v46, v[114:115], off
	v_lshl_add_u64 v[114:115], v[114:115], 0, s[100:101]
	global_load_dword v47, v[114:115], off
	v_lshl_add_u64 v[114:115], v[114:115], 0, s[100:101]
	global_load_dword v48, v[114:115], off
	v_lshl_add_u64 v[114:115], v[114:115], 0, s[100:101]
	global_load_dword v49, v[114:115], off
	v_lshl_add_u64 v[114:115], v[114:115], 0, s[100:101]
	global_load_dword v50, v[114:115], off
	v_lshl_add_u64 v[114:115], v[114:115], 0, s[100:101]
	global_load_dword v51, v[114:115], off
	v_lshl_add_u64 v[114:115], v[114:115], 0, s[100:101]
	global_load_dword v52, v[114:115], off
	v_lshl_add_u64 v[114:115], v[114:115], 0, s[100:101]
	global_load_dword v53, v[114:115], off
	v_lshl_add_u64 v[114:115], v[114:115], 0, s[100:101]
	global_load_dword v54, v[114:115], off
	v_lshl_add_u64 v[114:115], v[114:115], 0, s[100:101]
	global_load_dword v55, v[114:115], off
	v_lshl_add_u64 v[114:115], v[114:115], 0, s[100:101]
	global_load_dword v56, v[114:115], off
	v_lshl_add_u64 v[114:115], v[114:115], 0, s[100:101]
	global_load_dword v57, v[114:115], off
	v_lshl_add_u64 v[114:115], v[114:115], 0, s[100:101]
	global_load_dword v58, v[114:115], off
	v_lshl_add_u64 v[114:115], v[114:115], 0, s[100:101]
	global_load_dword v59, v[114:115], off
	s_cbranch_vccnz .LBB0_397
	s_mul_i32 s30, s16, 0x1600
	s_mul_hi_i32 s25, s16, 0x1600
	s_add_u32 s30, s44, s30
	s_addc_u32 s31, s45, s25
	v_lshl_add_u64 v[12:13], v[10:11], 1, s[30:31]
	v_add_co_u32_e32 v14, vcc, 0xffffd000, v12
	s_nop 1
	v_addc_co_u32_e32 v15, vcc, -1, v13, vcc
	global_load_dword v16, v[14:15], off offset:-2048
	v_add_co_u32_e32 v14, vcc, 0xffffe000, v12
	s_nop 1
	v_addc_co_u32_e32 v15, vcc, -1, v13, vcc
	global_load_dword v14, v[14:15], off offset:-512
	s_nop 0
	global_load_dword v15, v[12:13], off offset:-3072
	s_waitcnt vmcnt(0)
	v_lshlrev_b32_e32 v12, 16, v16
	v_and_b32_e32 v13, 0xffff0000, v16
	v_lshlrev_b32_e32 v16, 16, v14
	v_and_b32_e32 v17, 0xffff0000, v14
	v_lshlrev_b32_e32 v14, 16, v15
	v_and_b32_e32 v15, 0xffff0000, v15
	s_branch .LBB0_398
